# v5 + attention main loop: LDS-DMA pieces issued in QK gaps 2,4,6 instead of 9-11
# baseline (speedup 1.0000x reference)
.LBB0_832:
	v_cvt_pk_bf16_f32 v172, v104, v105
	v_cvt_pk_bf16_f32 v180, v96, v97
	s_add_i32 s12, s67, -3
	s_and_b32 s22, s12, 3
	s_mulk_i32 s22, 0x3000
	v_add_u32_e32 v0, s22, v214
	ds_read_b128 v[2:5], v0 offset:4096
	v_add_u32_e32 v14, s62, v217
	s_waitcnt lgkmcnt(4)
	v_mfma_f32_32x32x16_bf16 v[128:143], v[196:199], v[176:179], v[64:79]
	v_add_f32_e32 v6, v96, v97
	v_add_f32_e32 v6, v98, v6
	v_add_f32_e32 v6, v99, v6
	v_add_f32_e32 v10, v100, v6
	ds_read_b128 v[6:9], v0 offset:4608
	s_waitcnt lgkmcnt(4)
	v_mfma_f32_32x32x16_bf16 v[112:127], v[184:187], v[176:179], v[64:79]
	v_add_f32_e32 v10, v101, v10
	v_add_f32_e32 v10, v102, v10
	v_add_f32_e32 v15, v103, v10
	v_cvt_pk_bf16_f32 v181, v98, v99
	s_add_u32 s62, s58, 0xffff0000
	s_addc_u32 s63, s59, -1
	s_and_b32 s12, s67, 3
	s_mulk_i32 s12, 0x3000
	s_add_i32 s64, s12, s78
	s_mov_b32 m0, s64
	s_nop 0
	global_load_lds_dwordx4 v216, s[62:63]
	ds_read_b128 v[10:13], v0 offset:6144
	s_waitcnt lgkmcnt(4)
	v_mfma_f32_32x32x16_bf16 v[128:143], v[188:191], v[168:171], v[128:143]
	v_add_f32_e32 v15, v104, v15
	v_add_f32_e32 v15, v105, v15
	v_add_f32_e32 v15, v106, v15
	v_cvt_pk_bf16_f32 v182, v100, v101
	ds_read_b128 v[96:99], v0 offset:6656
	s_waitcnt lgkmcnt(4)
	v_mfma_f32_32x32x16_bf16 v[112:127], v[192:195], v[168:171], v[112:127]
	v_add_f32_e32 v15, v107, v15
	v_add_f32_e32 v15, v108, v15
	v_add_f32_e32 v15, v109, v15
	v_cvt_pk_bf16_f32 v183, v102, v103
	s_add_u32 s62, s60, 0xfffff000
	s_addc_u32 s63, s61, -1
	s_add_i32 s12, s12, s85
	s_mov_b32 m0, s12
	s_nop 0
	global_load_lds_dwordx4 v216, s[62:63]
	ds_read_b128 v[100:103], v0 offset:8192
	s_waitcnt lgkmcnt(4)
	v_mfma_f32_32x32x16_bf16 v[128:143], v[2:5], v[164:167], v[128:143]
	v_add_f32_e32 v15, v110, v15
	v_add_f32_e32 v15, v111, v15
	v_add_f32_e32 v15, v80, v15
	ds_read_b128 v[2:5], v0 offset:8704
	s_waitcnt lgkmcnt(4)
	v_mfma_f32_32x32x16_bf16 v[112:127], v[6:9], v[164:167], v[112:127]
	v_add_f32_e32 v15, v81, v15
	v_add_f32_e32 v15, v82, v15
	v_add_f32_e32 v15, v83, v15
	v_cvt_pk_bf16_f32 v173, v106, v107
	s_add_u32 s62, s6, 0xffff0000
	s_addc_u32 s63, s7, -1
	s_add_i32 s12, s23, s86
	s_mov_b32 m0, s12
	s_nop 0
	global_load_lds_dwordx4 v216, s[62:63]
	ds_read_b128 v[104:107], v0 offset:10240
	s_waitcnt lgkmcnt(4)
	v_mfma_f32_32x32x16_bf16 v[128:143], v[10:13], v[156:159], v[128:143]
	v_add_f32_e32 v6, v84, v15
	v_add_f32_e32 v6, v85, v6
	v_cvt_pk_bf16_f32 v174, v108, v109
	v_cvt_pk_bf16_f32 v175, v110, v111
	ds_read_b128 v[108:111], v0 offset:10752
	s_waitcnt lgkmcnt(4)
	v_mfma_f32_32x32x16_bf16 v[112:127], v[96:99], v[156:159], v[112:127]
	v_add_f32_e32 v0, v86, v6
	v_add_f32_e32 v0, v87, v0
	v_cvt_pk_bf16_f32 v160, v80, v81
	v_cvt_pk_bf16_f32 v161, v82, v83
	ds_read_b64_tr_b16 v[6:7], v14 offset:49152
	ds_read_b64_tr_b16 v[8:9], v14 offset:49664
	s_waitcnt lgkmcnt(5)
	v_mfma_f32_32x32x16_bf16 v[128:143], v[100:103], v[148:151], v[128:143]
	v_add_f32_e32 v0, v88, v0
	v_add_f32_e32 v0, v89, v0
	v_cvt_pk_bf16_f32 v162, v84, v85
	v_cvt_pk_bf16_f32 v163, v86, v87
	ds_read_b64_tr_b16 v[10:11], v14 offset:53248
	ds_read_b64_tr_b16 v[12:13], v14 offset:53760
	s_waitcnt lgkmcnt(6)
	v_mfma_f32_32x32x16_bf16 v[112:127], v[2:5], v[148:151], v[112:127]
	v_add_f32_e32 v0, v90, v0
	v_add_f32_e32 v0, v91, v0
	v_cvt_pk_bf16_f32 v152, v88, v89
	v_cvt_pk_bf16_f32 v153, v90, v91
	ds_read_b64_tr_b16 v[80:81], v14 offset:50176
	ds_read_b64_tr_b16 v[82:83], v14 offset:50688
	s_waitcnt lgkmcnt(7)
	v_mfma_f32_32x32x16_bf16 v[128:143], v[104:107], v[144:147], v[128:143]
	v_add_f32_e32 v0, v92, v0
	v_add_f32_e32 v0, v93, v0
	v_cvt_pk_bf16_f32 v154, v92, v93
	ds_read_b64_tr_b16 v[2:3], v14 offset:54272
	ds_read_b64_tr_b16 v[4:5], v14 offset:54784
	s_waitcnt lgkmcnt(8)
	v_mfma_f32_32x32x16_bf16 v[112:127], v[108:111], v[144:147], v[112:127]
	v_add_f32_e32 v0, v94, v0
	v_add_f32_e32 v0, v95, v0
	v_cvt_pk_bf16_f32 v155, v94, v95
	s_nop 1
	v_max_f32_e32 v15, v128, v129
	s_add_i32 s12, s67, -2
	s_and_b32 s12, s12, 3
	s_mulk_i32 s12, 0x3000
	s_nop 2
	v_max3_f32 v84, v130, v131, v113
	v_max3_f32 v15, v15, v112, v114
	v_max3_f32 v15, v15, v115, v132
	v_max3_f32 v84, v84, v134, v135
	v_max3_f32 v15, v15, v133, v116
	v_max3_f32 v84, v84, v118, v119
	v_max3_f32 v15, v15, v117, v136
	v_max3_f32 v84, v84, v138, v139
	v_max3_f32 v15, v15, v137, v120
	v_max3_f32 v84, v84, v122, v123
	v_max3_f32 v15, v15, v121, v140
	v_max3_f32 v84, v84, v142, v143
	v_max3_f32 v15, v15, v141, v124
	v_max3_f32 v84, v84, v126, v127
	v_max3_f32 v15, v15, v125, v84
	v_mov_b32_e32 v84, v15
	s_nop 1
	v_permlane32_swap_b32_e32 v15, v84
	v_max_f32_e32 v15, v15, v84
	v_cmp_lt_f32_e32 vcc, s94, v15
	s_cmp_lg_u64 vcc, 0
	v_add_f32_e32 v0, v218, v0
	s_cselect_b64 s[62:63], -1, 0
	s_cbranch_vccnz .LBB0_840

.LBB0_835:
	s_add_i32 s12, s23, 0x2000
	s_cmpk_lg_i32 s23, 0x4000
	s_cselect_b32 s12, s12, 0
	ds_read_b128 v[188:191], v15 offset:4096
	v_add_u32_e32 v14, s10, v217
	s_waitcnt lgkmcnt(4)
	v_mfma_f32_32x32x16_bf16 v[96:111], v[2:5], v[176:179], v[64:79]
	v_add_f32_e32 v80, v128, v129
	v_add_f32_e32 v80, v130, v80
	v_add_f32_e32 v80, v131, v80
	v_add_f32_e32 v80, v132, v80
	v_cvt_pk_bf16_f32 v180, v128, v129
	ds_read_b128 v[2:5], v15 offset:4608
	v_add_f32_e32 v80, v133, v80
	v_add_f32_e32 v80, v134, v80
	v_add_f32_e32 v128, v135, v80
	s_waitcnt lgkmcnt(4)
	v_mfma_f32_32x32x16_bf16 v[80:95], v[6:9], v[176:179], v[64:79]
	v_cvt_pk_bf16_f32 v181, v130, v131
	s_add_i32 s10, s22, s78
	s_mov_b32 m0, s10
	s_nop 0
	global_load_lds_dwordx4 v216, s[58:59]
	ds_read_b128 v[6:9], v15 offset:6144
	s_waitcnt lgkmcnt(4)
	v_mfma_f32_32x32x16_bf16 v[96:111], v[10:13], v[168:171], v[96:111]
	v_add_f32_e32 v128, v136, v128
	v_add_f32_e32 v128, v137, v128
	v_add_f32_e32 v128, v138, v128
	v_cvt_pk_bf16_f32 v182, v132, v133
	ds_read_b128 v[10:13], v15 offset:6656
	s_waitcnt lgkmcnt(4)
	v_mfma_f32_32x32x16_bf16 v[80:95], v[184:187], v[168:171], v[80:95]
	v_add_f32_e32 v128, v139, v128
	v_add_f32_e32 v128, v140, v128
	v_add_f32_e32 v132, v141, v128
	v_cvt_pk_bf16_f32 v183, v134, v135
	s_add_i32 s10, s22, s85
	s_mov_b32 m0, s10
	s_nop 0
	global_load_lds_dwordx4 v216, s[60:61]
	ds_read_b128 v[128:131], v15 offset:8192
	s_waitcnt lgkmcnt(4)
	v_mfma_f32_32x32x16_bf16 v[96:111], v[188:191], v[164:167], v[96:111]
	v_add_f32_e32 v132, v142, v132
	v_add_f32_e32 v132, v143, v132
	v_add_f32_e32 v152, v112, v132
	v_cvt_pk_bf16_f32 v172, v136, v137
	ds_read_b128 v[132:135], v15 offset:8704
	s_waitcnt lgkmcnt(4)
	v_mfma_f32_32x32x16_bf16 v[80:95], v[2:5], v[164:167], v[80:95]
	v_add_f32_e32 v136, v113, v152
	v_add_f32_e32 v136, v114, v136
	v_add_f32_e32 v136, v115, v136
	v_cvt_pk_bf16_f32 v173, v138, v139
	s_add_i32 s10, s12, s86
	s_mov_b32 m0, s10
	s_nop 0
	global_load_lds_dwordx4 v216, s[6:7]
	ds_read_b128 v[2:5], v15 offset:10240
	s_waitcnt lgkmcnt(4)
	v_mfma_f32_32x32x16_bf16 v[96:111], v[6:9], v[156:159], v[96:111]
	v_add_f32_e32 v136, v116, v136
	v_add_f32_e32 v152, v117, v136
	v_cvt_pk_bf16_f32 v174, v140, v141
	v_cvt_pk_bf16_f32 v175, v142, v143
	ds_read_b128 v[136:139], v15 offset:10752
	s_waitcnt lgkmcnt(4)
	v_mfma_f32_32x32x16_bf16 v[80:95], v[10:13], v[156:159], v[80:95]
	v_add_f32_e32 v6, v118, v152
	v_add_f32_e32 v6, v119, v6
	v_cvt_pk_bf16_f32 v160, v112, v113
	v_cvt_pk_bf16_f32 v161, v114, v115
	ds_read_b64_tr_b16 v[112:113], v14 offset:49152
	ds_read_b64_tr_b16 v[114:115], v14 offset:49664
	s_waitcnt lgkmcnt(5)
	v_mfma_f32_32x32x16_bf16 v[96:111], v[128:131], v[148:151], v[96:111]
	v_add_f32_e32 v6, v120, v6
	v_add_f32_e32 v6, v121, v6
	v_cvt_pk_bf16_f32 v162, v116, v117
	v_cvt_pk_bf16_f32 v163, v118, v119
	ds_read_b64_tr_b16 v[10:11], v14 offset:53248
	ds_read_b64_tr_b16 v[12:13], v14 offset:53760
	s_waitcnt lgkmcnt(6)
	v_mfma_f32_32x32x16_bf16 v[80:95], v[132:135], v[148:151], v[80:95]
	v_add_f32_e32 v6, v122, v6
	v_add_f32_e32 v15, v123, v6
	v_cvt_pk_bf16_f32 v152, v120, v121
	v_cvt_pk_bf16_f32 v153, v122, v123
	ds_read_b64_tr_b16 v[6:7], v14 offset:50176
	ds_read_b64_tr_b16 v[8:9], v14 offset:50688
	s_waitcnt lgkmcnt(7)
	v_mfma_f32_32x32x16_bf16 v[96:111], v[2:5], v[144:147], v[96:111]
	v_add_f32_e32 v15, v124, v15
	v_add_f32_e32 v15, v125, v15
	v_cvt_pk_bf16_f32 v154, v124, v125
	ds_read_b64_tr_b16 v[2:3], v14 offset:54272
	ds_read_b64_tr_b16 v[4:5], v14 offset:54784
	s_waitcnt lgkmcnt(8)
	v_mfma_f32_32x32x16_bf16 v[80:95], v[136:139], v[144:147], v[80:95]
	v_add_f32_e32 v15, v126, v15
	v_add_f32_e32 v15, v127, v15
	v_cvt_pk_bf16_f32 v155, v126, v127
	s_nop 1
	v_max_f32_e32 v116, v96, v97
	s_add_i32 s10, s67, -1
	s_and_b32 s22, s10, 3
	s_mulk_i32 s22, 0x3000
	s_nop 2
	v_max3_f32 v117, v98, v99, v81
	v_max3_f32 v116, v116, v80, v82
	v_max3_f32 v116, v116, v83, v100
	v_max3_f32 v117, v117, v102, v103
	v_max3_f32 v116, v116, v101, v84
	v_max3_f32 v117, v117, v86, v87
	v_max3_f32 v116, v116, v85, v104
	v_max3_f32 v117, v117, v106, v107
	v_max3_f32 v116, v116, v105, v88
	v_max3_f32 v117, v117, v90, v91
	v_max3_f32 v116, v116, v89, v108
	v_max3_f32 v117, v117, v110, v111
	v_max3_f32 v116, v116, v109, v92
	v_max3_f32 v117, v117, v94, v95
	v_add_f32_e32 v218, v0, v15
	v_max3_f32 v0, v116, v93, v117
	v_mov_b32_e32 v15, v0
	s_nop 1
	v_permlane32_swap_b32_e32 v0, v15
	v_max_f32_e32 v0, v0, v15
	v_cmp_lt_f32_e32 vcc, s94, v0
	s_cmp_lg_u64 vcc, 0
	s_cselect_b64 s[62:63], -1, 0
	s_cbranch_vccnz .LBB0_843
